# POST layer 0: blocks 0..63 (third GEMM tile) skip the row-wise recompute pass, other 448 blocks share all rows
# baseline (speedup 1.0000x reference)
; DI int TIDX() { int t = threadIdx.x; asm volatile("" : "+v"(t)); return t; }
; DI int BIDX() { int b = blockIdx.x; asm volatile("" : "+s"(b)); return b; }
; DI void rows_norm_mod(const P& p, const float* xlat, const float* xctx, int l, const float* gain, int sh_idx, int sc_idx,
;                       h16* dst, int nrows) {
;   const int lane = TIDX() & 63;
;   const int gw = BIDX() * 4 + (TIDX() >> 6), nw = gridDim.x * 4;
;   const float* mod = (const float*)(p.ws + OFF_MOD);
;   for (int row = gw; row < nrows; row += nw) {
.LBB0_155:
	v_mov_b32_e32 v0, v203
	s_mov_b32 s0, s31
	s_cmp_lg_u32 s36, 0x8800
	s_cbranch_scc1 .Lpost_rows_a
	s_cmp_lt_u32 s31, 64
	s_cbranch_scc1 .LBB0_160
	s_sub_i32 s0, s31, 64
.Lpost_rows_a:
	v_mov_b32_e32 v2, v203
	s_lshl_b32 s8, s0, 2
	v_ashrrev_i32_e32 v2, 6, v2
	v_add_u32_e32 v3, s8, v2
	v_cmp_gt_i32_e32 vcc, s36, v3
	s_and_saveexec_b64 s[0:1], vcc
	s_cbranch_execz .LBB0_160
	v_readlane_b32 s6, v252, 5
	v_readlane_b32 s7, v252, 6
	s_load_dword s4, s[6:7], 0x10
	s_nop 0
	s_load_dword s6, s[6:7], 0x0
	v_readlane_b32 s12, v254, 53
	v_lshlrev_b32_e32 v0, 2, v0
	v_readlane_b32 s24, v255, 1
	s_waitcnt lgkmcnt(0)
	s_lshr_b32 s4, s4, 16
	s_cmp_lg_u32 s4, 0
	s_cselect_b64 s[4:5], -1, 0
	s_cmp_lg_u64 s[4:5], 0
	s_addc_u32 s4, s6, 0
	s_cmp_lg_u32 s36, 0x8800
	s_cbranch_scc1 .Lpost_rows_b
	s_sub_i32 s4, s4, 64
.Lpost_rows_b:
	s_lshl_b32 s4, s4, 2
	s_add_u32 s6, s48, 0x2340000
	s_addc_u32 s7, s49, 0
	s_lshl_b32 s5, s78, 12
	v_readlane_b32 s25, v255, 2
	s_add_u32 s10, s24, s5
	v_and_b32_e32 v4, 0xfc, v0
	s_addc_u32 s11, s25, 0
	v_lshlrev_b32_e32 v0, 2, v4
	v_ashrrev_i32_e32 v3, 31, v2
	s_ashr_i32 s9, s8, 31
	v_lshl_add_u64 v[18:19], s[10:11], 0, v[0:1]
	v_lshlrev_b32_e32 v0, 1, v4
	v_lshl_add_u64 v[22:23], v[2:3], 0, s[8:9]
	v_or_b32_e32 v6, 0x100, v4
	v_or_b32_e32 v8, 0x200, v4
	v_or_b32_e32 v10, 0x300, v4
	v_lshl_add_u64 v[12:13], s[48:49], 0, v[0:1]
	s_mov_b64 s[10:11], 0x17cec000
	s_ashr_i32 s5, s4, 31
	v_lshlrev_b64 v[2:3], 12, v[22:23]
	v_lshl_add_u64 v[20:21], v[12:13], 0, s[10:11]
	v_lshl_add_u64 v[24:25], s[82:83], 0, v[2:3]
	s_lshl_b64 s[8:9], s[4:5], 12
	s_mov_b64 s[10:11], 0
	v_lshlrev_b32_e32 v0, 2, v4
	v_lshlrev_b32_e32 v26, 2, v6
	v_lshlrev_b32_e32 v28, 2, v8
	v_lshlrev_b32_e32 v30, 2, v10
	v_readlane_b32 s13, v254, 54
	v_readlane_b32 s14, v254, 55
	v_readlane_b32 s15, v254, 56
	v_readlane_b32 s16, v254, 57
	v_readlane_b32 s17, v254, 58
	v_readlane_b32 s18, v254, 59
	v_readlane_b32 s19, v254, 60
	v_readlane_b32 s20, v254, 61
	v_readlane_b32 s21, v254, 62
	v_readlane_b32 s22, v254, 63
	v_readlane_b32 s23, v255, 0
	v_readlane_b32 s26, v255, 3
	v_readlane_b32 s27, v255, 4
	s_branch .LBB0_158
